# attention P*V LDS reads prefetched/pipelined, K/V staging batched, S5 rewrite
# speedup vs baseline: 1.0030x; 1.0030x over previous
.LBB0_742:
	v_mov_b32_e32 v44, s33
	v_cndmask_b32_e64 v44, v38, v44, s[62:63]
	v_cndmask_b32_e64 v38, v44, v38, s[56:57]
	v_max_f32_e32 v44, v53, v53
	v_max_f32_e32 v45, v61, v61
	v_max_f32_e32 v44, v45, v44
	v_max_f32_e32 v45, v42, v42
	v_max_f32_e32 v62, v43, v43
	v_max_f32_e32 v45, v62, v45
	v_max3_f32 v44, v58, v44, v45
	v_max_f32_e32 v45, v37, v37
	v_max_f32_e32 v62, v36, v36
	v_max_f32_e32 v45, v62, v45
	v_max_f32_e32 v62, v33, v33
	v_max_f32_e32 v63, v32, v32
	v_max_f32_e32 v62, v63, v62
	v_max3_f32 v45, v34, v35, v45
	v_max3_f32 v62, v30, v31, v62
	v_max3_f32 v44, v44, v45, v62
	v_max_f32_e32 v45, v29, v29
	v_max_f32_e32 v62, v28, v28
	v_max_f32_e32 v45, v62, v45
	v_max_f32_e32 v62, v25, v25
	v_max_f32_e32 v63, v24, v24
	v_max_f32_e32 v62, v63, v62
	v_max3_f32 v45, v26, v27, v45
	v_max3_f32 v62, v22, v23, v62
	v_max3_f32 v44, v44, v45, v62
	v_max_f32_e32 v45, v21, v21
	v_max_f32_e32 v62, v20, v20
	v_max_f32_e32 v45, v62, v45
	v_max_f32_e32 v62, v17, v17
	v_max_f32_e32 v63, v16, v16
	v_max_f32_e32 v62, v63, v62
	v_max3_f32 v45, v18, v19, v45
	v_max3_f32 v62, v14, v15, v62
	v_cndmask_b32_e64 v40, v40, v211, s[60:61]
	v_cndmask_b32_e64 v41, v41, v211, s[58:59]
	v_max3_f32 v44, v44, v45, v62
	v_max_f32_e32 v45, v13, v13
	v_max_f32_e32 v62, v12, v12
	v_max_f32_e32 v45, v62, v45
	v_max_f32_e32 v62, v41, v41
	v_max_f32_e32 v63, v40, v40
	v_cndmask_b32_e64 v39, v211, v39, s[56:57]
	v_max_f32_e32 v62, v63, v62
	v_max3_f32 v45, v10, v11, v45
	v_max3_f32 v62, v38, v39, v62
	v_max3_f32 v44, v44, v45, v62
	ds_bpermute_b32 v45, v56, v44
	s_waitcnt lgkmcnt(0)
	v_max_f32_e32 v45, v45, v45
	v_max_f32_e32 v44, v44, v45
	ds_bpermute_b32 v45, v55, v44
	s_waitcnt lgkmcnt(0)
	v_max_f32_e32 v45, v45, v45
	v_max_f32_e32 v44, v44, v45
	v_sub_f32_e32 v45, v61, v44
	v_exp_f32_e32 v45, v45
	v_sub_f32_e32 v53, v53, v44
	v_exp_f32_e32 v53, v53
	v_sub_f32_e32 v43, v43, v44
	v_exp_f32_e32 v43, v43
	v_sub_f32_e32 v42, v42, v44
	v_exp_f32_e32 v42, v42
	v_sub_f32_e32 v34, v34, v44
	v_add_f32_e32 v61, 0, v45
	v_exp_f32_e32 v34, v34
	v_sub_f32_e32 v35, v35, v44
	v_add_f32_e32 v61, v53, v61
	v_exp_f32_e32 v35, v35
	v_sub_f32_e32 v36, v36, v44
	v_add_f32_e32 v61, v43, v61
	v_exp_f32_e32 v36, v36
	v_sub_f32_e32 v37, v37, v44
	v_add_f32_e32 v61, v42, v61
	v_exp_f32_e32 v37, v37
	v_sub_f32_e32 v30, v30, v44
	v_add_f32_e32 v61, v34, v61
	v_exp_f32_e32 v66, v30
	v_add_f32_e32 v61, v35, v61
	v_add_f32_e32 v61, v36, v61
	v_add_f32_e32 v61, v37, v61
	v_sub_f32_e32 v31, v31, v44
	v_add_f32_e32 v30, v66, v61
	v_exp_f32_e32 v61, v31
	v_sub_f32_e32 v31, v32, v44
	v_exp_f32_e32 v67, v31
	v_sub_f32_e32 v31, v33, v44
	v_exp_f32_e32 v68, v31
	v_sub_f32_e32 v26, v26, v44
	v_exp_f32_e32 v69, v26
	v_sub_f32_e32 v27, v27, v44
	v_add_f32_e32 v30, v61, v30
	v_exp_f32_e32 v70, v27
	v_sub_f32_e32 v27, v28, v44
	v_add_f32_e32 v30, v67, v30
	v_exp_f32_e32 v71, v27
	v_sub_f32_e32 v27, v29, v44
	v_add_f32_e32 v30, v68, v30
	v_exp_f32_e32 v72, v27
	v_add_f32_e32 v26, v69, v30
	v_add_f32_e32 v26, v70, v26
	v_add_f32_e32 v26, v71, v26
	v_sub_f32_e32 v22, v22, v44
	v_add_f32_e32 v27, v72, v26
	v_exp_f32_e32 v26, v22
	v_sub_f32_e32 v23, v23, v44
	v_sub_f32_e32 v18, v18, v44
	v_exp_f32_e32 v73, v18
	v_add_f32_e32 v22, v26, v27
	v_exp_f32_e32 v27, v23
	v_sub_f32_e32 v23, v24, v44
	v_exp_f32_e32 v24, v23
	v_sub_f32_e32 v23, v25, v44
	v_exp_f32_e32 v25, v23
	v_sub_f32_e32 v19, v19, v44
	v_add_f32_e32 v22, v27, v22
	v_exp_f32_e32 v74, v19
	v_sub_f32_e32 v19, v20, v44
	v_add_f32_e32 v22, v24, v22
	v_exp_f32_e32 v75, v19
	v_sub_f32_e32 v19, v21, v44
	v_add_f32_e32 v22, v25, v22
	v_exp_f32_e32 v76, v19
	v_add_f32_e32 v18, v73, v22
	v_add_f32_e32 v18, v74, v18
	v_add_f32_e32 v18, v75, v18
	v_sub_f32_e32 v14, v14, v44
	v_add_f32_e32 v19, v76, v18
	v_exp_f32_e32 v18, v14
	v_sub_f32_e32 v15, v15, v44
	v_exp_f32_e32 v15, v15
	v_sub_f32_e32 v16, v16, v44
	v_exp_f32_e32 v16, v16
	v_sub_f32_e32 v17, v17, v44
	v_exp_f32_e32 v17, v17
	v_sub_f32_e32 v10, v10, v44
	v_add_f32_e32 v14, v18, v19
	v_exp_f32_e32 v19, v10
	v_sub_f32_e32 v11, v11, v44
	v_add_f32_e32 v14, v15, v14
	v_exp_f32_e32 v20, v11
	v_sub_f32_e32 v11, v12, v44
	v_add_f32_e32 v14, v16, v14
	v_exp_f32_e32 v21, v11
	v_sub_f32_e32 v11, v13, v44
	v_add_f32_e32 v14, v17, v14
	v_exp_f32_e32 v22, v11
	v_sub_f32_e32 v11, v38, v44
	v_add_f32_e32 v10, v19, v14
	v_exp_f32_e32 v11, v11
	v_sub_f32_e32 v12, v39, v44
	v_add_f32_e32 v10, v20, v10
	v_exp_f32_e32 v12, v12
	v_sub_f32_e32 v13, v40, v44
	v_add_f32_e32 v10, v21, v10
	v_exp_f32_e32 v13, v13
	v_sub_f32_e32 v14, v41, v44
	v_add_f32_e32 v10, v22, v10
	v_exp_f32_e32 v14, v14
	v_add_f32_e32 v10, v11, v10
	v_add_f32_e32 v10, v12, v10
	v_add_f32_e32 v10, v13, v10
	v_add_f32_e32 v10, v14, v10
	v_add_u32_e32 v142, s79, v49
	v_add_u32_e32 v142, 0x11000, v142
	ds_read_b64 v[78:79], v142
	ds_read_b64 v[80:81], v142 offset:32
	ds_read_b64 v[82:83], v142 offset:8448
	ds_read_b64 v[84:85], v142 offset:8480
	ds_read_b64 v[86:87], v142 offset:16896
	ds_read_b64 v[88:89], v142 offset:16928
	ds_read_b64 v[90:91], v142 offset:25344
	ds_read_b64 v[92:93], v142 offset:25376
	ds_read_b64 v[94:95], v142 offset:64
	ds_read_b64 v[96:97], v142 offset:96
	ds_read_b64 v[98:99], v142 offset:8512
	ds_read_b64 v[100:101], v142 offset:8544
	ds_read_b64 v[102:103], v142 offset:16960
	ds_read_b64 v[104:105], v142 offset:16992
	ds_bpermute_b32 v23, v56, v10
	v_cvt_pk_bf16_f32 v28, v45, v53
	v_cvt_pk_bf16_f32 v29, v43, v42
	v_cvt_pk_bf16_f32 v30, v34, v35
	v_cvt_pk_bf16_f32 v31, v36, v37
	v_cvt_pk_bf16_f32 v62, v66, v61
	v_cvt_pk_bf16_f32 v63, v67, v68
	v_cvt_pk_bf16_f32 v64, v69, v70
	v_cvt_pk_bf16_f32 v65, v71, v72
	s_waitcnt lgkmcnt(0)
	v_add_f32_e32 v10, v10, v23
	ds_bpermute_b32 v23, v55, v10
	v_ashrrev_i32_e32 v53, 31, v52
	ds_read_b64 v[106:107], v142 offset:25408
	ds_read_b64 v[108:109], v142 offset:25440
	ds_read_b64 v[110:111], v142 offset:128
	ds_read_b64 v[112:113], v142 offset:160
	ds_read_b64 v[114:115], v142 offset:8576
	ds_read_b64 v[116:117], v142 offset:8608
	v_cvt_pk_bf16_f32 v34, v26, v27
	v_cvt_pk_bf16_f32 v35, v24, v25
	v_cvt_pk_bf16_f32 v36, v73, v74
	v_cvt_pk_bf16_f32 v37, v75, v76
	v_cvt_pk_bf16_f32 v66, v18, v15
	v_cvt_pk_bf16_f32 v67, v16, v17
	v_cvt_pk_bf16_f32 v68, v19, v20
	v_cvt_pk_bf16_f32 v69, v21, v22
	v_cvt_pk_bf16_f32 v162, v11, v12
	v_cvt_pk_bf16_f32 v163, v13, v14
	s_waitcnt lgkmcnt(6)
	v_add_f32_e32 v10, v10, v23
	v_sub_f32_e32 v23, v58, v44
	v_exp_f32_e32 v23, v23
	s_nop 0
	v_add_f32_e32 v10, v23, v10
	v_mfma_f32_16x16x32_bf16 v[146:149], v[78:81], v[28:31], 0
	v_rcp_f32_e32 v10, v10
	v_mfma_f32_16x16x32_bf16 v[150:153], v[82:85], v[28:31], 0
	v_mfma_f32_16x16x32_bf16 v[154:157], v[86:89], v[28:31], 0
	v_mfma_f32_16x16x32_bf16 v[158:161], v[90:93], v[28:31], 0
	ds_read_b64 v[118:119], v142 offset:17024
	ds_read_b64 v[120:121], v142 offset:17056
	ds_read_b64 v[122:123], v142 offset:25472
	ds_read_b64 v[124:125], v142 offset:25504
	ds_read_b64 v[126:127], v142 offset:192
	ds_read_b64 v[128:129], v142 offset:224
	ds_read_b64 v[130:131], v142 offset:8640
	ds_read_b64 v[132:133], v142 offset:8672
	s_waitcnt lgkmcnt(12)
	v_mfma_f32_16x16x32_bf16 v[146:149], v[94:97], v[62:65], v[146:149]
	v_mfma_f32_16x16x32_bf16 v[150:153], v[98:101], v[62:65], v[150:153]
	v_mfma_f32_16x16x32_bf16 v[154:157], v[102:105], v[62:65], v[154:157]
	v_mfma_f32_16x16x32_bf16 v[158:161], v[106:109], v[62:65], v[158:161]
	s_waitcnt lgkmcnt(4)
	ds_read_b64 v[134:135], v142 offset:17088
	ds_read_b64 v[136:137], v142 offset:17120
	ds_read_b64 v[138:139], v142 offset:25536
	ds_read_b64 v[140:141], v142 offset:25568
	ds_read_b64 v[78:79], v142 offset:256
	ds_read_b64 v[80:81], v142 offset:8704
	ds_read_b64 v[82:83], v142 offset:17152
	ds_read_b64 v[84:85], v142 offset:25600
	v_mfma_f32_16x16x32_bf16 v[146:149], v[110:113], v[34:37], v[146:149]
	v_mfma_f32_16x16x32_bf16 v[150:153], v[114:117], v[34:37], v[150:153]
	v_mfma_f32_16x16x32_bf16 v[154:157], v[118:121], v[34:37], v[154:157]
	v_mfma_f32_16x16x32_bf16 v[158:161], v[122:125], v[34:37], v[158:161]
	s_waitcnt lgkmcnt(4)
	v_mfma_f32_16x16x32_bf16 v[146:149], v[126:129], v[66:69], v[146:149]
	v_mfma_f32_16x16x32_bf16 v[150:153], v[130:133], v[66:69], v[150:153]
	v_mfma_f32_16x16x32_bf16 v[154:157], v[134:137], v[66:69], v[154:157]
	v_mfma_f32_16x16x32_bf16 v[158:161], v[138:141], v[66:69], v[158:161]
	s_waitcnt lgkmcnt(0)
	v_mfma_f32_16x16x16_bf16 v[12:15], v[78:79], v[162:163], v[146:149]
	v_mfma_f32_16x16x16_bf16 v[16:19], v[80:81], v[162:163], v[150:153]
	v_mfma_f32_16x16x16_bf16 v[24:27], v[82:83], v[162:163], v[154:157]
	v_mfma_f32_16x16x16_bf16 v[20:23], v[84:85], v[162:163], v[158:161]
	s_nop 7
	v_mul_f32_e64 v14, v10, v14
	v_mul_f32_e64 v15, v10, v15
	v_pk_mul_f32 v[12:13], v[10:11], v[12:13] op_sel_hi:[0,1]
	v_mul_f32_e32 v11, v13, v13
	v_fmac_f32_e32 v11, v12, v12
	v_mul_f32_e32 v32, v15, v15
	v_fmac_f32_e32 v32, v14, v14
	v_cvt_pk_bf16_f32 v12, v12, v13
	v_cvt_pk_bf16_f32 v13, v14, v15
	v_add_f32_e32 v11, v11, v32
	s_nop 1
	v_lshlrev_b64 v[28:29], 11, v[52:53]
	v_lshl_add_u64 v[28:29], s[92:93], 0, v[28:29]
	v_lshl_add_u64 v[28:29], s[6:7], 1, v[28:29]
	v_lshl_add_u64 v[28:29], v[28:29], 0, v[0:1]
	v_add_co_u32_e32 v14, vcc, s13, v28
	v_lshl_add_u64 v[30:31], v[28:29], 0, s[96:97]
	s_nop 0
	v_addc_co_u32_e32 v15, vcc, 0, v29, vcc
	global_store_dwordx2 v[14:15], v[12:13], off offset:1024
	v_pk_mul_f32 v[12:13], v[10:11], v[18:19] op_sel_hi:[0,1]
	v_pk_mul_f32 v[14:15], v[10:11], v[16:17] op_sel_hi:[0,1]
	v_mul_f32_e32 v16, v15, v15
	v_mul_f32_e32 v17, v13, v13
	v_fmac_f32_e32 v16, v14, v14
	v_fmac_f32_e32 v17, v12, v12
	v_add_f32_e32 v16, v16, v17
	v_add_f32_e32 v11, v11, v16
	v_cvt_pk_bf16_f32 v14, v14, v15
	v_cvt_pk_bf16_f32 v15, v12, v13
	global_store_dwordx2 v[30:31], v[14:15], off offset:32
	v_pk_mul_f32 v[12:13], v[10:11], v[26:27] op_sel_hi:[0,1]
	v_pk_mul_f32 v[14:15], v[10:11], v[24:25] op_sel_hi:[0,1]
	v_mul_f32_e32 v16, v15, v15
	v_mul_f32_e32 v17, v13, v13
	v_fmac_f32_e32 v16, v14, v14
	v_fmac_f32_e32 v17, v12, v12
	v_add_f32_e32 v16, v16, v17
	v_add_f32_e32 v16, v11, v16
	v_cvt_pk_bf16_f32 v14, v14, v15
	v_cvt_pk_bf16_f32 v15, v12, v13
	v_pk_mul_f32 v[12:13], v[10:11], v[22:23] op_sel_hi:[0,1]
	v_pk_mul_f32 v[10:11], v[10:11], v[20:21] op_sel_hi:[0,1]
	global_store_dwordx2 v[30:31], v[14:15], off offset:64
	v_mul_f32_e32 v14, v11, v11
	v_mul_f32_e32 v15, v13, v13
	v_fmac_f32_e32 v14, v10, v10
	v_fmac_f32_e32 v15, v12, v12
	v_add_f32_e32 v14, v14, v15
	v_add_f32_e32 v14, v16, v14
	v_cvt_pk_bf16_f32 v10, v10, v11
	v_cvt_pk_bf16_f32 v11, v12, v13
	global_store_dwordx2 v[30:31], v[10:11], off offset:96
	ds_bpermute_b32 v10, v56, v14
	s_waitcnt lgkmcnt(0)
	v_add_f32_e32 v10, v14, v10
	ds_bpermute_b32 v11, v55, v10
	s_and_saveexec_b64 s[68:69], s[52:53]
	s_cbranch_execz .LBB0_738
	s_waitcnt lgkmcnt(0)
	v_add_f32_e32 v10, v10, v11
	v_mul_f32_e32 v10, 0x4d800000, v10
	v_trunc_f32_e32 v10, v10
	v_mul_f32_e32 v11, 0x2f800000, v10
	v_floor_f32_e32 v11, v11
	v_fmac_f32_e32 v10, 0xcf800000, v11
	v_cvt_u32_f32_e32 v10, v10
	v_cvt_u32_f32_e32 v11, v11
	v_lshl_add_u64 v[12:13], v[52:53], 3, s[50:51]
	global_atomic_add_x2 v[12:13], v[10:11], off
	s_branch .LBB0_738
